# K-loops: counter / pointer bumps / exit test moved in front of the loop-back barrier (only the branch stays behind it)
# baseline (speedup 1.0000x reference)
.LBB0_178:
	ds_read_b128 v[148:151], v171
	ds_read_b128 v[152:155], v171 offset:1024
	ds_read_b128 v[156:159], v171 offset:2048
	ds_read_b128 v[160:163], v171 offset:3072
	ds_read_b128 v[190:193], v173
	ds_read_b128 v[198:201], v173 offset:1024
	ds_read_b128 v[202:205], v173 offset:2048
	ds_read_b128 v[206:209], v173 offset:3072
	s_add_u32 s54, s52, 0xfffc0080
	s_addc_u32 s55, s53, -1
	s_cmp_eq_u32 s87, 12
	s_cselect_b32 s57, s5, s55
	s_cselect_b32 s56, s10, s54
	s_cselect_b32 s55, s11, s86
	s_cselect_b32 s54, s39, s41
	v_lshl_add_u64 v[166:167], s[52:53], 0, v[140:141]
	s_add_i32 m0, s49, 0xc000
	ds_read_b128 v[210:213], v177
	ds_read_b128 v[214:217], v177 offset:1024
	ds_read_b128 v[218:221], v177 offset:2048
	ds_read_b128 v[222:225], v177 offset:3072
	ds_read_b128 v[226:229], v177 offset:4096
	ds_read_b128 v[230:233], v177 offset:5120
	ds_read_b128 v[234:237], v177 offset:6144
	ds_read_b128 v[238:241], v177 offset:7168
	global_load_lds_dwordx4 v[166:167], off
	v_lshl_add_u64 v[166:167], s[52:53], 0, v[142:143]
	s_add_i32 m0, s49, 0xe000
	s_nop 0
	global_load_lds_dwordx4 v[166:167], off
	s_waitcnt vmcnt(8)
	s_waitcnt lgkmcnt(0)
	s_barrier
	s_setprio 1
	s_waitcnt lgkmcnt(0)
	v_mfma_f32_16x16x32_bf16 v[124:127], v[148:151], v[210:213], v[124:127]
	v_mfma_f32_16x16x32_bf16 v[120:123], v[156:159], v[210:213], v[120:123]
	v_mfma_f32_16x16x32_bf16 v[108:111], v[148:151], v[218:221], v[108:111]
	v_mfma_f32_16x16x32_bf16 v[104:107], v[156:159], v[218:221], v[104:107]
	v_mfma_f32_16x16x32_bf16 v[92:95], v[148:151], v[226:229], v[92:95]
	v_mfma_f32_16x16x32_bf16 v[88:91], v[156:159], v[226:229], v[88:91]
	v_mfma_f32_16x16x32_bf16 v[76:79], v[148:151], v[234:237], v[76:79]
	v_mfma_f32_16x16x32_bf16 v[72:75], v[156:159], v[234:237], v[72:75]
	v_mfma_f32_16x16x32_bf16 v[124:127], v[152:155], v[214:217], v[124:127]
	v_mfma_f32_16x16x32_bf16 v[120:123], v[160:163], v[214:217], v[120:123]
	v_mfma_f32_16x16x32_bf16 v[108:111], v[152:155], v[222:225], v[108:111]
	v_mfma_f32_16x16x32_bf16 v[104:107], v[160:163], v[222:225], v[104:107]
	v_mfma_f32_16x16x32_bf16 v[92:95], v[152:155], v[230:233], v[92:95]
	v_mfma_f32_16x16x32_bf16 v[88:91], v[160:163], v[230:233], v[88:91]
	v_mfma_f32_16x16x32_bf16 v[76:79], v[152:155], v[238:241], v[76:79]
	v_mfma_f32_16x16x32_bf16 v[72:75], v[160:163], v[238:241], v[72:75]
	s_setprio 0
	s_setprio 1
	v_mfma_f32_16x16x32_bf16 v[116:119], v[190:193], v[210:213], v[116:119]
	v_mfma_f32_16x16x32_bf16 v[112:115], v[202:205], v[210:213], v[112:115]
	v_mfma_f32_16x16x32_bf16 v[100:103], v[190:193], v[218:221], v[100:103]
	v_mfma_f32_16x16x32_bf16 v[96:99], v[202:205], v[218:221], v[96:99]
	v_mfma_f32_16x16x32_bf16 v[84:87], v[190:193], v[226:229], v[84:87]
	v_mfma_f32_16x16x32_bf16 v[80:83], v[202:205], v[226:229], v[80:83]
	v_mfma_f32_16x16x32_bf16 v[68:71], v[190:193], v[234:237], v[68:71]
	v_mfma_f32_16x16x32_bf16 v[64:67], v[202:205], v[234:237], v[64:67]
	v_mfma_f32_16x16x32_bf16 v[116:119], v[198:201], v[214:217], v[116:119]
	v_mfma_f32_16x16x32_bf16 v[112:115], v[206:209], v[214:217], v[112:115]
	v_mfma_f32_16x16x32_bf16 v[100:103], v[198:201], v[222:225], v[100:103]
	v_mfma_f32_16x16x32_bf16 v[96:99], v[206:209], v[222:225], v[96:99]
	v_mfma_f32_16x16x32_bf16 v[84:87], v[198:201], v[230:233], v[84:87]
	v_mfma_f32_16x16x32_bf16 v[80:83], v[206:209], v[230:233], v[80:83]
	v_mfma_f32_16x16x32_bf16 v[68:71], v[198:201], v[238:241], v[68:71]
	v_mfma_f32_16x16x32_bf16 v[64:67], v[206:209], v[238:241], v[64:67]
	s_setprio 0
	s_barrier
	s_add_i32 s88, s81, s64
	v_lshl_add_u64 v[166:167], s[54:55], 0, v[130:131]
	s_mov_b32 m0, s88
	ds_read_b128 v[210:213], v177 offset:16384
	ds_read_b128 v[214:217], v177 offset:17408
	ds_read_b128 v[218:221], v177 offset:18432
	ds_read_b128 v[222:225], v177 offset:19456
	ds_read_b128 v[226:229], v177 offset:20480
	ds_read_b128 v[230:233], v177 offset:21504
	ds_read_b128 v[234:237], v177 offset:22528
	ds_read_b128 v[238:241], v177 offset:23552
	global_load_lds_dwordx4 v[166:167], off
	s_add_i32 m0, s88, 0x2000
	s_add_u32 s90, s54, 0x40000
	v_lshl_add_u64 v[174:175], s[54:55], 0, v[134:135]
	s_addc_u32 s91, s55, 0
	s_add_i32 s88, s82, s64
	global_load_lds_dwordx4 v[174:175], off
	v_lshl_add_u64 v[178:179], s[90:91], 0, v[130:131]
	s_mov_b32 m0, s88
	v_lshl_add_u64 v[182:183], s[56:57], 0, v[132:133]
	global_load_lds_dwordx4 v[178:179], off
	v_lshl_add_u64 v[178:179], s[90:91], 0, v[134:135]
	s_add_i32 m0, s88, 0x2000
	s_nop 0
	global_load_lds_dwordx4 v[178:179], off
	v_lshl_add_u64 v[178:179], s[56:57], 0, v[128:129]
	s_mov_b32 m0, s49
	s_nop 0
	global_load_lds_dwordx4 v[178:179], off
	s_mov_b32 m0, s65
	s_nop 0
	global_load_lds_dwordx4 v[182:183], off
	s_waitcnt vmcnt(8)
	s_waitcnt lgkmcnt(0)
	s_barrier
	s_setprio 1
	s_waitcnt lgkmcnt(0)
	v_mfma_f32_16x16x32_bf16 v[60:63], v[148:151], v[210:213], v[60:63]
	v_mfma_f32_16x16x32_bf16 v[56:59], v[156:159], v[210:213], v[56:59]
	v_mfma_f32_16x16x32_bf16 v[44:47], v[148:151], v[218:221], v[44:47]
	v_mfma_f32_16x16x32_bf16 v[40:43], v[156:159], v[218:221], v[40:43]
	v_mfma_f32_16x16x32_bf16 v[28:31], v[148:151], v[226:229], v[28:31]
	v_mfma_f32_16x16x32_bf16 v[24:27], v[156:159], v[226:229], v[24:27]
	v_mfma_f32_16x16x32_bf16 v[12:15], v[148:151], v[234:237], v[12:15]
	v_mfma_f32_16x16x32_bf16 v[8:11], v[156:159], v[234:237], v[8:11]
	v_mfma_f32_16x16x32_bf16 v[60:63], v[152:155], v[214:217], v[60:63]
	v_mfma_f32_16x16x32_bf16 v[56:59], v[160:163], v[214:217], v[56:59]
	v_mfma_f32_16x16x32_bf16 v[44:47], v[152:155], v[222:225], v[44:47]
	v_mfma_f32_16x16x32_bf16 v[40:43], v[160:163], v[222:225], v[40:43]
	v_mfma_f32_16x16x32_bf16 v[28:31], v[152:155], v[230:233], v[28:31]
	v_mfma_f32_16x16x32_bf16 v[24:27], v[160:163], v[230:233], v[24:27]
	v_mfma_f32_16x16x32_bf16 v[12:15], v[152:155], v[238:241], v[12:15]
	v_mfma_f32_16x16x32_bf16 v[8:11], v[160:163], v[238:241], v[8:11]
	s_setprio 0
	s_setprio 1
	v_mfma_f32_16x16x32_bf16 v[52:55], v[190:193], v[210:213], v[52:55]
	v_mfma_f32_16x16x32_bf16 v[48:51], v[202:205], v[210:213], v[48:51]
	v_mfma_f32_16x16x32_bf16 v[36:39], v[190:193], v[218:221], v[36:39]
	v_mfma_f32_16x16x32_bf16 v[32:35], v[202:205], v[218:221], v[32:35]
	v_mfma_f32_16x16x32_bf16 v[20:23], v[190:193], v[226:229], v[20:23]
	v_mfma_f32_16x16x32_bf16 v[16:19], v[202:205], v[226:229], v[16:19]
	v_mfma_f32_16x16x32_bf16 v[4:7], v[190:193], v[234:237], v[4:7]
	v_mfma_f32_16x16x32_bf16 v[0:3], v[202:205], v[234:237], v[0:3]
	v_mfma_f32_16x16x32_bf16 v[52:55], v[198:201], v[214:217], v[52:55]
	v_mfma_f32_16x16x32_bf16 v[48:51], v[206:209], v[214:217], v[48:51]
	v_mfma_f32_16x16x32_bf16 v[36:39], v[198:201], v[222:225], v[36:39]
	v_mfma_f32_16x16x32_bf16 v[32:35], v[206:209], v[222:225], v[32:35]
	v_mfma_f32_16x16x32_bf16 v[20:23], v[198:201], v[230:233], v[20:23]
	v_mfma_f32_16x16x32_bf16 v[16:19], v[206:209], v[230:233], v[16:19]
	v_mfma_f32_16x16x32_bf16 v[4:7], v[198:201], v[238:241], v[4:7]
	v_mfma_f32_16x16x32_bf16 v[0:3], v[206:209], v[238:241], v[0:3]
	s_setprio 0
	s_barrier
	s_add_i32 s88, 0, 0x18000
	v_add_u32_e32 v136, s88, v169
	s_add_i32 s90, 0, 0x1c000
	ds_read_b128 v[148:151], v136
	ds_read_b128 v[152:155], v136 offset:1024
	ds_read_b128 v[156:159], v136 offset:2048
	ds_read_b128 v[160:163], v136 offset:3072
	v_add_u32_e32 v136, s90, v169
	ds_read_b128 v[190:193], v136
	ds_read_b128 v[198:201], v136 offset:1024
	ds_read_b128 v[202:205], v136 offset:2048
	ds_read_b128 v[206:209], v136 offset:3072
	s_add_u32 s56, s56, 0x40000
	s_addc_u32 s57, s57, 0
	s_mov_b32 m0, s66
	v_lshl_add_u64 v[186:187], s[56:57], 0, v[128:129]
	ds_read_b128 v[210:213], v177 offset:32768
	ds_read_b128 v[214:217], v177 offset:33792
	ds_read_b128 v[218:221], v177 offset:34816
	ds_read_b128 v[222:225], v177 offset:35840
	ds_read_b128 v[226:229], v177 offset:36864
	ds_read_b128 v[230:233], v177 offset:37888
	ds_read_b128 v[234:237], v177 offset:38912
	ds_read_b128 v[238:241], v177 offset:39936
	global_load_lds_dwordx4 v[186:187], off
	v_lshl_add_u64 v[186:187], s[56:57], 0, v[132:133]
	s_mov_b32 m0, s67
	s_nop 0
	global_load_lds_dwordx4 v[186:187], off
	s_waitcnt vmcnt(8)
	s_waitcnt lgkmcnt(0)
	s_barrier
	s_setprio 1
	s_waitcnt lgkmcnt(0)
	v_mfma_f32_16x16x32_bf16 v[124:127], v[148:151], v[210:213], v[124:127]
	v_mfma_f32_16x16x32_bf16 v[120:123], v[156:159], v[210:213], v[120:123]
	v_mfma_f32_16x16x32_bf16 v[108:111], v[148:151], v[218:221], v[108:111]
	v_mfma_f32_16x16x32_bf16 v[104:107], v[156:159], v[218:221], v[104:107]
	v_mfma_f32_16x16x32_bf16 v[92:95], v[148:151], v[226:229], v[92:95]
	v_mfma_f32_16x16x32_bf16 v[88:91], v[156:159], v[226:229], v[88:91]
	v_mfma_f32_16x16x32_bf16 v[76:79], v[148:151], v[234:237], v[76:79]
	v_mfma_f32_16x16x32_bf16 v[72:75], v[156:159], v[234:237], v[72:75]
	v_mfma_f32_16x16x32_bf16 v[124:127], v[152:155], v[214:217], v[124:127]
	v_mfma_f32_16x16x32_bf16 v[120:123], v[160:163], v[214:217], v[120:123]
	v_mfma_f32_16x16x32_bf16 v[108:111], v[152:155], v[222:225], v[108:111]
	v_mfma_f32_16x16x32_bf16 v[104:107], v[160:163], v[222:225], v[104:107]
	v_mfma_f32_16x16x32_bf16 v[92:95], v[152:155], v[230:233], v[92:95]
	v_mfma_f32_16x16x32_bf16 v[88:91], v[160:163], v[230:233], v[88:91]
	v_mfma_f32_16x16x32_bf16 v[76:79], v[152:155], v[238:241], v[76:79]
	v_mfma_f32_16x16x32_bf16 v[72:75], v[160:163], v[238:241], v[72:75]
	s_setprio 0
	s_setprio 1
	v_mfma_f32_16x16x32_bf16 v[116:119], v[190:193], v[210:213], v[116:119]
	v_mfma_f32_16x16x32_bf16 v[112:115], v[202:205], v[210:213], v[112:115]
	v_mfma_f32_16x16x32_bf16 v[100:103], v[190:193], v[218:221], v[100:103]
	v_mfma_f32_16x16x32_bf16 v[96:99], v[202:205], v[218:221], v[96:99]
	v_mfma_f32_16x16x32_bf16 v[84:87], v[190:193], v[226:229], v[84:87]
	v_mfma_f32_16x16x32_bf16 v[80:83], v[202:205], v[226:229], v[80:83]
	v_mfma_f32_16x16x32_bf16 v[68:71], v[190:193], v[234:237], v[68:71]
	v_mfma_f32_16x16x32_bf16 v[64:67], v[202:205], v[234:237], v[64:67]
	v_mfma_f32_16x16x32_bf16 v[116:119], v[198:201], v[214:217], v[116:119]
	v_mfma_f32_16x16x32_bf16 v[112:115], v[206:209], v[214:217], v[112:115]
	v_mfma_f32_16x16x32_bf16 v[100:103], v[198:201], v[222:225], v[100:103]
	v_mfma_f32_16x16x32_bf16 v[96:99], v[206:209], v[222:225], v[96:99]
	v_mfma_f32_16x16x32_bf16 v[84:87], v[198:201], v[230:233], v[84:87]
	v_mfma_f32_16x16x32_bf16 v[80:83], v[206:209], v[230:233], v[80:83]
	v_mfma_f32_16x16x32_bf16 v[68:71], v[198:201], v[238:241], v[68:71]
	v_mfma_f32_16x16x32_bf16 v[64:67], v[206:209], v[238:241], v[64:67]
	s_setprio 0
	s_barrier
	s_add_i32 s56, s88, s64
	v_lshl_add_u64 v[166:167], v[166:167], 0, s[14:15]
	s_mov_b32 m0, s56
	ds_read_b128 v[210:213], v177 offset:49152
	ds_read_b128 v[214:217], v177 offset:50176
	ds_read_b128 v[218:221], v177 offset:51200
	ds_read_b128 v[222:225], v177 offset:52224
	ds_read_b128 v[226:229], v177 offset:53248
	ds_read_b128 v[230:233], v177 offset:54272
	ds_read_b128 v[234:237], v177 offset:55296
	ds_read_b128 v[238:241], v177 offset:56320
	global_load_lds_dwordx4 v[166:167], off
	s_add_i32 m0, s56, 0x2000
	s_add_u32 s54, s54, 0x40080
	v_lshl_add_u64 v[166:167], v[174:175], 0, s[14:15]
	s_addc_u32 s55, s55, 0
	s_add_i32 s56, s90, s64
	global_load_lds_dwordx4 v[166:167], off
	v_lshl_add_u64 v[166:167], s[54:55], 0, v[130:131]
	s_mov_b32 m0, s56
	s_nop 0
	global_load_lds_dwordx4 v[166:167], off
	v_lshl_add_u64 v[166:167], s[54:55], 0, v[134:135]
	s_add_i32 m0, s56, 0x2000
	s_nop 0
	global_load_lds_dwordx4 v[166:167], off
	v_lshl_add_u64 v[166:167], v[178:179], 0, s[14:15]
	s_mov_b32 m0, s76
	s_nop 0
	global_load_lds_dwordx4 v[166:167], off
	v_lshl_add_u64 v[166:167], v[182:183], 0, s[14:15]
	s_mov_b32 m0, s77
	s_nop 0
	global_load_lds_dwordx4 v[166:167], off
	s_waitcnt vmcnt(8)
	s_waitcnt lgkmcnt(0)
	s_barrier
	s_setprio 1
	s_waitcnt lgkmcnt(0)
	v_mfma_f32_16x16x32_bf16 v[60:63], v[148:151], v[210:213], v[60:63]
	v_mfma_f32_16x16x32_bf16 v[56:59], v[156:159], v[210:213], v[56:59]
	v_mfma_f32_16x16x32_bf16 v[44:47], v[148:151], v[218:221], v[44:47]
	v_mfma_f32_16x16x32_bf16 v[40:43], v[156:159], v[218:221], v[40:43]
	v_mfma_f32_16x16x32_bf16 v[28:31], v[148:151], v[226:229], v[28:31]
	v_mfma_f32_16x16x32_bf16 v[24:27], v[156:159], v[226:229], v[24:27]
	v_mfma_f32_16x16x32_bf16 v[12:15], v[148:151], v[234:237], v[12:15]
	v_mfma_f32_16x16x32_bf16 v[8:11], v[156:159], v[234:237], v[8:11]
	v_mfma_f32_16x16x32_bf16 v[60:63], v[152:155], v[214:217], v[60:63]
	v_mfma_f32_16x16x32_bf16 v[56:59], v[160:163], v[214:217], v[56:59]
	v_mfma_f32_16x16x32_bf16 v[44:47], v[152:155], v[222:225], v[44:47]
	v_mfma_f32_16x16x32_bf16 v[40:43], v[160:163], v[222:225], v[40:43]
	v_mfma_f32_16x16x32_bf16 v[28:31], v[152:155], v[230:233], v[28:31]
	v_mfma_f32_16x16x32_bf16 v[24:27], v[160:163], v[230:233], v[24:27]
	v_mfma_f32_16x16x32_bf16 v[12:15], v[152:155], v[238:241], v[12:15]
	v_mfma_f32_16x16x32_bf16 v[8:11], v[160:163], v[238:241], v[8:11]
	s_setprio 0
	s_setprio 1
	v_mfma_f32_16x16x32_bf16 v[52:55], v[190:193], v[210:213], v[52:55]
	v_mfma_f32_16x16x32_bf16 v[48:51], v[202:205], v[210:213], v[48:51]
	v_mfma_f32_16x16x32_bf16 v[36:39], v[190:193], v[218:221], v[36:39]
	v_mfma_f32_16x16x32_bf16 v[32:35], v[202:205], v[218:221], v[32:35]
	v_mfma_f32_16x16x32_bf16 v[20:23], v[190:193], v[226:229], v[20:23]
	v_mfma_f32_16x16x32_bf16 v[16:19], v[202:205], v[226:229], v[16:19]
	v_mfma_f32_16x16x32_bf16 v[4:7], v[190:193], v[234:237], v[4:7]
	v_mfma_f32_16x16x32_bf16 v[0:3], v[202:205], v[234:237], v[0:3]
	v_mfma_f32_16x16x32_bf16 v[52:55], v[198:201], v[214:217], v[52:55]
	v_mfma_f32_16x16x32_bf16 v[48:51], v[206:209], v[214:217], v[48:51]
	v_mfma_f32_16x16x32_bf16 v[36:39], v[198:201], v[222:225], v[36:39]
	v_mfma_f32_16x16x32_bf16 v[32:35], v[206:209], v[222:225], v[32:35]
	v_mfma_f32_16x16x32_bf16 v[20:23], v[198:201], v[230:233], v[20:23]
	v_mfma_f32_16x16x32_bf16 v[16:19], v[206:209], v[230:233], v[16:19]
	v_mfma_f32_16x16x32_bf16 v[4:7], v[198:201], v[238:241], v[4:7]
	v_mfma_f32_16x16x32_bf16 v[0:3], v[206:209], v[238:241], v[0:3]
	s_add_i32 s87, s87, 2
	s_add_u32 s52, s52, 0x100
	s_addc_u32 s53, s53, 0
	s_add_u32 s41, s41, 0x100
	s_addc_u32 s86, s86, 0
	s_cmp_gt_u32 s87, 13
	s_setprio 0
	s_barrier
	s_cbranch_scc0 .LBB0_178
	s_and_b64 vcc, exec, s[16:17]
	s_cbranch_vccz .LBB0_181
	s_barrier

.LBB0_492:
	ds_read_b128 v[96:99], v222
	ds_read_b128 v[108:111], v222 offset:1024
	ds_read_b128 v[120:123], v222 offset:2048
	ds_read_b128 v[128:131], v222 offset:3072
	ds_read_b128 v[144:147], v223
	ds_read_b128 v[148:151], v223 offset:1024
	ds_read_b128 v[152:155], v223 offset:2048
	ds_read_b128 v[156:159], v223 offset:3072
	s_add_u32 s46, s44, 0xfffc0080
	s_addc_u32 s47, s45, -1
	s_cmp_eq_u32 s72, 12
	s_cselect_b32 s49, s10, s47
	s_cselect_b32 s48, s11, s46
	s_cselect_b32 s47, s35, s67
	s_cselect_b32 s46, s37, s43
	v_lshl_add_u64 v[210:211], s[44:45], 0, v[192:193]
	s_add_i32 m0, s54, 0xc000
	ds_read_b128 v[160:163], v224
	ds_read_b128 v[164:167], v224 offset:1024
	ds_read_b128 v[168:171], v224 offset:2048
	ds_read_b128 v[172:175], v224 offset:3072
	ds_read_b128 v[176:179], v224 offset:4096
	ds_read_b128 v[180:183], v224 offset:5120
	ds_read_b128 v[202:205], v224 offset:6144
	ds_read_b128 v[206:209], v224 offset:7168
	global_load_lds_dwordx4 v[210:211], off
	v_lshl_add_u64 v[210:211], s[44:45], 0, v[194:195]
	s_add_i32 m0, s54, 0xe000
	s_nop 0
	global_load_lds_dwordx4 v[210:211], off
	s_waitcnt vmcnt(8)
	s_waitcnt lgkmcnt(0)
	s_barrier
	s_setprio 1
	s_waitcnt lgkmcnt(0)
	v_mfma_f32_16x16x32_bf16 v[140:143], v[96:99], v[160:163], v[140:143]
	v_mfma_f32_16x16x32_bf16 v[136:139], v[120:123], v[160:163], v[136:139]
	v_mfma_f32_16x16x32_bf16 v[116:119], v[96:99], v[168:171], v[116:119]
	v_mfma_f32_16x16x32_bf16 v[112:115], v[120:123], v[168:171], v[112:115]
	v_mfma_f32_16x16x32_bf16 v[92:95], v[96:99], v[176:179], v[92:95]
	v_mfma_f32_16x16x32_bf16 v[88:91], v[120:123], v[176:179], v[88:91]
	v_mfma_f32_16x16x32_bf16 v[76:79], v[96:99], v[202:205], v[76:79]
	v_mfma_f32_16x16x32_bf16 v[72:75], v[120:123], v[202:205], v[72:75]
	v_mfma_f32_16x16x32_bf16 v[140:143], v[108:111], v[164:167], v[140:143]
	v_mfma_f32_16x16x32_bf16 v[136:139], v[128:131], v[164:167], v[136:139]
	v_mfma_f32_16x16x32_bf16 v[116:119], v[108:111], v[172:175], v[116:119]
	v_mfma_f32_16x16x32_bf16 v[112:115], v[128:131], v[172:175], v[112:115]
	v_mfma_f32_16x16x32_bf16 v[92:95], v[108:111], v[180:183], v[92:95]
	v_mfma_f32_16x16x32_bf16 v[88:91], v[128:131], v[180:183], v[88:91]
	v_mfma_f32_16x16x32_bf16 v[76:79], v[108:111], v[206:209], v[76:79]
	v_mfma_f32_16x16x32_bf16 v[72:75], v[128:131], v[206:209], v[72:75]
	s_setprio 0
	s_setprio 1
	v_mfma_f32_16x16x32_bf16 v[132:135], v[144:147], v[160:163], v[132:135]
	v_mfma_f32_16x16x32_bf16 v[124:127], v[152:155], v[160:163], v[124:127]
	v_mfma_f32_16x16x32_bf16 v[104:107], v[144:147], v[168:171], v[104:107]
	v_mfma_f32_16x16x32_bf16 v[100:103], v[152:155], v[168:171], v[100:103]
	v_mfma_f32_16x16x32_bf16 v[84:87], v[144:147], v[176:179], v[84:87]
	v_mfma_f32_16x16x32_bf16 v[80:83], v[152:155], v[176:179], v[80:83]
	v_mfma_f32_16x16x32_bf16 v[68:71], v[144:147], v[202:205], v[68:71]
	v_mfma_f32_16x16x32_bf16 v[64:67], v[152:155], v[202:205], v[64:67]
	v_mfma_f32_16x16x32_bf16 v[132:135], v[148:151], v[164:167], v[132:135]
	v_mfma_f32_16x16x32_bf16 v[124:127], v[156:159], v[164:167], v[124:127]
	v_mfma_f32_16x16x32_bf16 v[104:107], v[148:151], v[172:175], v[104:107]
	v_mfma_f32_16x16x32_bf16 v[100:103], v[156:159], v[172:175], v[100:103]
	v_mfma_f32_16x16x32_bf16 v[84:87], v[148:151], v[180:183], v[84:87]
	v_mfma_f32_16x16x32_bf16 v[80:83], v[156:159], v[180:183], v[80:83]
	v_mfma_f32_16x16x32_bf16 v[68:71], v[148:151], v[206:209], v[68:71]
	v_mfma_f32_16x16x32_bf16 v[64:67], v[156:159], v[206:209], v[64:67]
	s_setprio 0
	s_barrier
	s_add_i32 s73, s64, s53
	v_lshl_add_u64 v[210:211], s[46:47], 0, v[186:187]
	s_mov_b32 m0, s73
	ds_read_b128 v[160:163], v224 offset:16384
	ds_read_b128 v[164:167], v224 offset:17408
	ds_read_b128 v[168:171], v224 offset:18432
	ds_read_b128 v[172:175], v224 offset:19456
	ds_read_b128 v[176:179], v224 offset:20480
	ds_read_b128 v[180:183], v224 offset:21504
	ds_read_b128 v[202:205], v224 offset:22528
	ds_read_b128 v[206:209], v224 offset:23552
	global_load_lds_dwordx4 v[210:211], off
	s_add_i32 m0, s73, 0x2000
	s_add_u32 s74, s46, 0x40000
	v_lshl_add_u64 v[212:213], s[46:47], 0, v[190:191]
	s_addc_u32 s75, s47, 0
	s_add_i32 s73, s65, s53
	global_load_lds_dwordx4 v[212:213], off
	v_lshl_add_u64 v[214:215], s[74:75], 0, v[186:187]
	s_mov_b32 m0, s73
	v_lshl_add_u64 v[216:217], s[48:49], 0, v[188:189]
	global_load_lds_dwordx4 v[214:215], off
	v_lshl_add_u64 v[214:215], s[74:75], 0, v[190:191]
	s_add_i32 m0, s73, 0x2000
	s_nop 0
	global_load_lds_dwordx4 v[214:215], off
	v_lshl_add_u64 v[214:215], s[48:49], 0, v[184:185]
	s_mov_b32 m0, s54
	s_nop 0
	global_load_lds_dwordx4 v[214:215], off
	s_mov_b32 m0, s55
	s_nop 0
	global_load_lds_dwordx4 v[216:217], off
	s_waitcnt vmcnt(8)
	s_waitcnt lgkmcnt(0)
	s_barrier
	s_setprio 1
	s_waitcnt lgkmcnt(0)
	v_mfma_f32_16x16x32_bf16 v[60:63], v[96:99], v[160:163], v[60:63]
	v_mfma_f32_16x16x32_bf16 v[56:59], v[120:123], v[160:163], v[56:59]
	v_mfma_f32_16x16x32_bf16 v[44:47], v[96:99], v[168:171], v[44:47]
	v_mfma_f32_16x16x32_bf16 v[40:43], v[120:123], v[168:171], v[40:43]
	v_mfma_f32_16x16x32_bf16 v[28:31], v[96:99], v[176:179], v[28:31]
	v_mfma_f32_16x16x32_bf16 v[24:27], v[120:123], v[176:179], v[24:27]
	v_mfma_f32_16x16x32_bf16 v[12:15], v[96:99], v[202:205], v[12:15]
	v_mfma_f32_16x16x32_bf16 v[8:11], v[120:123], v[202:205], v[8:11]
	v_mfma_f32_16x16x32_bf16 v[60:63], v[108:111], v[164:167], v[60:63]
	v_mfma_f32_16x16x32_bf16 v[56:59], v[128:131], v[164:167], v[56:59]
	v_mfma_f32_16x16x32_bf16 v[44:47], v[108:111], v[172:175], v[44:47]
	v_mfma_f32_16x16x32_bf16 v[40:43], v[128:131], v[172:175], v[40:43]
	v_mfma_f32_16x16x32_bf16 v[28:31], v[108:111], v[180:183], v[28:31]
	v_mfma_f32_16x16x32_bf16 v[24:27], v[128:131], v[180:183], v[24:27]
	v_mfma_f32_16x16x32_bf16 v[12:15], v[108:111], v[206:209], v[12:15]
	v_mfma_f32_16x16x32_bf16 v[8:11], v[128:131], v[206:209], v[8:11]
	s_setprio 0
	s_setprio 1
	v_mfma_f32_16x16x32_bf16 v[52:55], v[144:147], v[160:163], v[52:55]
	v_mfma_f32_16x16x32_bf16 v[48:51], v[152:155], v[160:163], v[48:51]
	v_mfma_f32_16x16x32_bf16 v[36:39], v[144:147], v[168:171], v[36:39]
	v_mfma_f32_16x16x32_bf16 v[32:35], v[152:155], v[168:171], v[32:35]
	v_mfma_f32_16x16x32_bf16 v[20:23], v[144:147], v[176:179], v[20:23]
	v_mfma_f32_16x16x32_bf16 v[16:19], v[152:155], v[176:179], v[16:19]
	v_mfma_f32_16x16x32_bf16 v[4:7], v[144:147], v[202:205], v[4:7]
	v_mfma_f32_16x16x32_bf16 v[0:3], v[152:155], v[202:205], v[0:3]
	v_mfma_f32_16x16x32_bf16 v[52:55], v[148:151], v[164:167], v[52:55]
	v_mfma_f32_16x16x32_bf16 v[48:51], v[156:159], v[164:167], v[48:51]
	v_mfma_f32_16x16x32_bf16 v[36:39], v[148:151], v[172:175], v[36:39]
	v_mfma_f32_16x16x32_bf16 v[32:35], v[156:159], v[172:175], v[32:35]
	v_mfma_f32_16x16x32_bf16 v[20:23], v[148:151], v[180:183], v[20:23]
	v_mfma_f32_16x16x32_bf16 v[16:19], v[156:159], v[180:183], v[16:19]
	v_mfma_f32_16x16x32_bf16 v[4:7], v[148:151], v[206:209], v[4:7]
	v_mfma_f32_16x16x32_bf16 v[0:3], v[156:159], v[206:209], v[0:3]
	s_setprio 0
	s_barrier
	s_add_i32 s73, 0, 0x18000
	s_add_i32 s74, 0, 0x1c000
	v_add_u32_e32 v128, s73, v220
	v_add_u32_e32 v156, s74, v220
	ds_read_b128 v[96:99], v128
	ds_read_b128 v[108:111], v128 offset:1024
	ds_read_b128 v[120:123], v128 offset:2048
	ds_read_b128 v[128:131], v128 offset:3072
	ds_read_b128 v[144:147], v156
	ds_read_b128 v[148:151], v156 offset:1024
	ds_read_b128 v[152:155], v156 offset:2048
	ds_read_b128 v[156:159], v156 offset:3072
	s_add_u32 s48, s48, 0x40000
	s_addc_u32 s49, s49, 0
	s_mov_b32 m0, s56
	v_lshl_add_u64 v[218:219], s[48:49], 0, v[184:185]
	ds_read_b128 v[160:163], v224 offset:32768
	ds_read_b128 v[164:167], v224 offset:33792
	ds_read_b128 v[168:171], v224 offset:34816
	ds_read_b128 v[172:175], v224 offset:35840
	ds_read_b128 v[176:179], v224 offset:36864
	ds_read_b128 v[180:183], v224 offset:37888
	ds_read_b128 v[202:205], v224 offset:38912
	ds_read_b128 v[206:209], v224 offset:39936
	global_load_lds_dwordx4 v[218:219], off
	v_lshl_add_u64 v[218:219], s[48:49], 0, v[188:189]
	s_mov_b32 m0, s57
	s_nop 0
	global_load_lds_dwordx4 v[218:219], off
	s_waitcnt vmcnt(8)
	s_waitcnt lgkmcnt(0)
	s_barrier
	s_setprio 1
	s_waitcnt lgkmcnt(0)
	v_mfma_f32_16x16x32_bf16 v[140:143], v[96:99], v[160:163], v[140:143]
	v_mfma_f32_16x16x32_bf16 v[136:139], v[120:123], v[160:163], v[136:139]
	v_mfma_f32_16x16x32_bf16 v[116:119], v[96:99], v[168:171], v[116:119]
	v_mfma_f32_16x16x32_bf16 v[112:115], v[120:123], v[168:171], v[112:115]
	v_mfma_f32_16x16x32_bf16 v[92:95], v[96:99], v[176:179], v[92:95]
	v_mfma_f32_16x16x32_bf16 v[88:91], v[120:123], v[176:179], v[88:91]
	v_mfma_f32_16x16x32_bf16 v[76:79], v[96:99], v[202:205], v[76:79]
	v_mfma_f32_16x16x32_bf16 v[72:75], v[120:123], v[202:205], v[72:75]
	v_mfma_f32_16x16x32_bf16 v[140:143], v[108:111], v[164:167], v[140:143]
	v_mfma_f32_16x16x32_bf16 v[136:139], v[128:131], v[164:167], v[136:139]
	v_mfma_f32_16x16x32_bf16 v[116:119], v[108:111], v[172:175], v[116:119]
	v_mfma_f32_16x16x32_bf16 v[112:115], v[128:131], v[172:175], v[112:115]
	v_mfma_f32_16x16x32_bf16 v[92:95], v[108:111], v[180:183], v[92:95]
	v_mfma_f32_16x16x32_bf16 v[88:91], v[128:131], v[180:183], v[88:91]
	v_mfma_f32_16x16x32_bf16 v[76:79], v[108:111], v[206:209], v[76:79]
	v_mfma_f32_16x16x32_bf16 v[72:75], v[128:131], v[206:209], v[72:75]
	s_setprio 0
	s_setprio 1
	v_mfma_f32_16x16x32_bf16 v[132:135], v[144:147], v[160:163], v[132:135]
	v_mfma_f32_16x16x32_bf16 v[124:127], v[152:155], v[160:163], v[124:127]
	v_mfma_f32_16x16x32_bf16 v[104:107], v[144:147], v[168:171], v[104:107]
	v_mfma_f32_16x16x32_bf16 v[100:103], v[152:155], v[168:171], v[100:103]
	v_mfma_f32_16x16x32_bf16 v[84:87], v[144:147], v[176:179], v[84:87]
	v_mfma_f32_16x16x32_bf16 v[80:83], v[152:155], v[176:179], v[80:83]
	v_mfma_f32_16x16x32_bf16 v[68:71], v[144:147], v[202:205], v[68:71]
	v_mfma_f32_16x16x32_bf16 v[64:67], v[152:155], v[202:205], v[64:67]
	v_mfma_f32_16x16x32_bf16 v[132:135], v[148:151], v[164:167], v[132:135]
	v_mfma_f32_16x16x32_bf16 v[124:127], v[156:159], v[164:167], v[124:127]
	v_mfma_f32_16x16x32_bf16 v[104:107], v[148:151], v[172:175], v[104:107]
	v_mfma_f32_16x16x32_bf16 v[100:103], v[156:159], v[172:175], v[100:103]
	v_mfma_f32_16x16x32_bf16 v[84:87], v[148:151], v[180:183], v[84:87]
	v_mfma_f32_16x16x32_bf16 v[80:83], v[156:159], v[180:183], v[80:83]
	v_mfma_f32_16x16x32_bf16 v[68:71], v[148:151], v[206:209], v[68:71]
	v_mfma_f32_16x16x32_bf16 v[64:67], v[156:159], v[206:209], v[64:67]
	s_setprio 0
	s_barrier
	s_add_i32 s48, s73, s53
	v_lshl_add_u64 v[210:211], v[210:211], 0, s[20:21]
	s_mov_b32 m0, s48
	ds_read_b128 v[160:163], v224 offset:49152
	ds_read_b128 v[164:167], v224 offset:50176
	ds_read_b128 v[168:171], v224 offset:51200
	ds_read_b128 v[172:175], v224 offset:52224
	ds_read_b128 v[176:179], v224 offset:53248
	ds_read_b128 v[180:183], v224 offset:54272
	ds_read_b128 v[202:205], v224 offset:55296
	ds_read_b128 v[206:209], v224 offset:56320
	global_load_lds_dwordx4 v[210:211], off
	s_add_i32 m0, s48, 0x2000
	s_add_u32 s46, s46, 0x40080
	v_lshl_add_u64 v[210:211], v[212:213], 0, s[20:21]
	s_addc_u32 s47, s47, 0
	s_add_i32 s48, s74, s53
	global_load_lds_dwordx4 v[210:211], off
	v_lshl_add_u64 v[210:211], s[46:47], 0, v[186:187]
	s_mov_b32 m0, s48
	s_nop 0
	global_load_lds_dwordx4 v[210:211], off
	v_lshl_add_u64 v[210:211], s[46:47], 0, v[190:191]
	s_add_i32 m0, s48, 0x2000
	s_nop 0
	global_load_lds_dwordx4 v[210:211], off
	v_lshl_add_u64 v[210:211], v[214:215], 0, s[20:21]
	s_mov_b32 m0, s59
	s_nop 0
	global_load_lds_dwordx4 v[210:211], off
	v_lshl_add_u64 v[210:211], v[216:217], 0, s[20:21]
	s_mov_b32 m0, s60
	s_nop 0
	global_load_lds_dwordx4 v[210:211], off
	s_waitcnt vmcnt(8)
	s_waitcnt lgkmcnt(0)
	s_barrier
	s_setprio 1
	s_waitcnt lgkmcnt(0)
	v_mfma_f32_16x16x32_bf16 v[60:63], v[96:99], v[160:163], v[60:63]
	v_mfma_f32_16x16x32_bf16 v[56:59], v[120:123], v[160:163], v[56:59]
	v_mfma_f32_16x16x32_bf16 v[44:47], v[96:99], v[168:171], v[44:47]
	v_mfma_f32_16x16x32_bf16 v[40:43], v[120:123], v[168:171], v[40:43]
	v_mfma_f32_16x16x32_bf16 v[28:31], v[96:99], v[176:179], v[28:31]
	v_mfma_f32_16x16x32_bf16 v[24:27], v[120:123], v[176:179], v[24:27]
	v_mfma_f32_16x16x32_bf16 v[12:15], v[96:99], v[202:205], v[12:15]
	v_mfma_f32_16x16x32_bf16 v[8:11], v[120:123], v[202:205], v[8:11]
	v_mfma_f32_16x16x32_bf16 v[60:63], v[108:111], v[164:167], v[60:63]
	v_mfma_f32_16x16x32_bf16 v[56:59], v[128:131], v[164:167], v[56:59]
	v_mfma_f32_16x16x32_bf16 v[44:47], v[108:111], v[172:175], v[44:47]
	v_mfma_f32_16x16x32_bf16 v[40:43], v[128:131], v[172:175], v[40:43]
	v_mfma_f32_16x16x32_bf16 v[28:31], v[108:111], v[180:183], v[28:31]
	v_mfma_f32_16x16x32_bf16 v[24:27], v[128:131], v[180:183], v[24:27]
	v_mfma_f32_16x16x32_bf16 v[12:15], v[108:111], v[206:209], v[12:15]
	v_mfma_f32_16x16x32_bf16 v[8:11], v[128:131], v[206:209], v[8:11]
	s_setprio 0
	s_setprio 1
	v_mfma_f32_16x16x32_bf16 v[52:55], v[144:147], v[160:163], v[52:55]
	v_mfma_f32_16x16x32_bf16 v[48:51], v[152:155], v[160:163], v[48:51]
	v_mfma_f32_16x16x32_bf16 v[36:39], v[144:147], v[168:171], v[36:39]
	v_mfma_f32_16x16x32_bf16 v[32:35], v[152:155], v[168:171], v[32:35]
	v_mfma_f32_16x16x32_bf16 v[20:23], v[144:147], v[176:179], v[20:23]
	v_mfma_f32_16x16x32_bf16 v[16:19], v[152:155], v[176:179], v[16:19]
	v_mfma_f32_16x16x32_bf16 v[4:7], v[144:147], v[202:205], v[4:7]
	v_mfma_f32_16x16x32_bf16 v[0:3], v[152:155], v[202:205], v[0:3]
	v_mfma_f32_16x16x32_bf16 v[52:55], v[148:151], v[164:167], v[52:55]
	v_mfma_f32_16x16x32_bf16 v[48:51], v[156:159], v[164:167], v[48:51]
	v_mfma_f32_16x16x32_bf16 v[36:39], v[148:151], v[172:175], v[36:39]
	v_mfma_f32_16x16x32_bf16 v[32:35], v[156:159], v[172:175], v[32:35]
	v_mfma_f32_16x16x32_bf16 v[20:23], v[148:151], v[180:183], v[20:23]
	v_mfma_f32_16x16x32_bf16 v[16:19], v[156:159], v[180:183], v[16:19]
	v_mfma_f32_16x16x32_bf16 v[4:7], v[148:151], v[206:209], v[4:7]
	v_mfma_f32_16x16x32_bf16 v[0:3], v[156:159], v[206:209], v[0:3]
	s_add_i32 s72, s72, 2
	s_add_u32 s44, s44, 0x100
	s_addc_u32 s45, s45, 0
	s_add_u32 s43, s43, 0x100
	s_addc_u32 s67, s67, 0
	s_cmp_gt_u32 s72, 13
	s_setprio 0
	s_barrier
	s_cbranch_scc0 .LBB0_492
	s_and_b64 vcc, exec, s[26:27]
	s_cbranch_vccz .LBB0_495
	s_barrier

.LBB0_577:
	ds_read_b128 v[108:111], v245
	ds_read_b128 v[116:119], v245 offset:1024
	ds_read_b128 v[120:123], v245 offset:2048
	ds_read_b128 v[124:127], v245 offset:3072
	ds_read_b128 v[128:131], v246
	ds_read_b128 v[132:135], v246 offset:1024
	ds_read_b128 v[136:139], v246 offset:2048
	ds_read_b128 v[140:143], v246 offset:3072
	s_add_u32 s62, s8, 0xfffc0080
	s_addc_u32 s63, s9, -1
	s_cmp_eq_u32 s86, 12
	s_cselect_b32 s65, s10, s63
	s_cselect_b32 s64, s11, s62
	s_cselect_b32 s63, s51, s61
	s_cselect_b32 s62, s53, s59
	v_lshl_add_u64 v[220:221], s[8:9], 0, v[212:213]
	s_add_i32 m0, s74, 0xc000
	ds_read_b128 v[144:147], v247
	ds_read_b128 v[148:151], v247 offset:1024
	ds_read_b128 v[168:171], v247 offset:2048
	ds_read_b128 v[172:175], v247 offset:3072
	ds_read_b128 v[176:179], v247 offset:4096
	ds_read_b128 v[180:183], v247 offset:5120
	ds_read_b128 v[184:187], v247 offset:6144
	ds_read_b128 v[188:191], v247 offset:7168
	global_load_lds_dwordx4 v[220:221], off
	v_lshl_add_u64 v[220:221], s[8:9], 0, v[214:215]
	s_add_i32 m0, s74, 0xe000
	s_nop 0
	global_load_lds_dwordx4 v[220:221], off
	s_waitcnt vmcnt(8)
	s_waitcnt lgkmcnt(0)
	s_barrier
	s_setprio 1
	s_waitcnt lgkmcnt(0)
	v_mfma_f32_16x16x32_bf16 v[52:55], v[108:111], v[144:147], v[52:55]
	v_mfma_f32_16x16x32_bf16 v[44:47], v[120:123], v[144:147], v[44:47]
	v_mfma_f32_16x16x32_bf16 v[164:167], v[108:111], v[168:171], v[164:167]
	v_mfma_f32_16x16x32_bf16 v[68:71], v[120:123], v[168:171], v[68:71]
	v_mfma_f32_16x16x32_bf16 v[160:163], v[108:111], v[176:179], v[160:163]
	v_mfma_f32_16x16x32_bf16 v[60:63], v[120:123], v[176:179], v[60:63]
	v_mfma_f32_16x16x32_bf16 v[84:87], v[108:111], v[184:187], v[84:87]
	v_mfma_f32_16x16x32_bf16 v[80:83], v[120:123], v[184:187], v[80:83]
	v_mfma_f32_16x16x32_bf16 v[52:55], v[116:119], v[148:151], v[52:55]
	v_mfma_f32_16x16x32_bf16 v[44:47], v[124:127], v[148:151], v[44:47]
	v_mfma_f32_16x16x32_bf16 v[164:167], v[116:119], v[172:175], v[164:167]
	v_mfma_f32_16x16x32_bf16 v[68:71], v[124:127], v[172:175], v[68:71]
	v_mfma_f32_16x16x32_bf16 v[160:163], v[116:119], v[180:183], v[160:163]
	v_mfma_f32_16x16x32_bf16 v[60:63], v[124:127], v[180:183], v[60:63]
	v_mfma_f32_16x16x32_bf16 v[84:87], v[116:119], v[188:191], v[84:87]
	v_mfma_f32_16x16x32_bf16 v[80:83], v[124:127], v[188:191], v[80:83]
	s_setprio 0
	s_setprio 1
	v_mfma_f32_16x16x32_bf16 v[36:39], v[128:131], v[144:147], v[36:39]
	v_mfma_f32_16x16x32_bf16 v[28:31], v[136:139], v[144:147], v[28:31]
	v_mfma_f32_16x16x32_bf16 v[64:67], v[136:139], v[168:171], v[64:67]
	v_mfma_f32_16x16x32_bf16 v[56:59], v[136:139], v[176:179], v[56:59]
	v_mfma_f32_16x16x32_bf16 v[76:79], v[128:131], v[184:187], v[76:79]
	v_mfma_f32_16x16x32_bf16 v[72:75], v[136:139], v[184:187], v[72:75]
	v_mfma_f32_16x16x32_bf16 v[36:39], v[132:135], v[148:151], v[36:39]
	v_mfma_f32_16x16x32_bf16 v[28:31], v[140:143], v[148:151], v[28:31]
	v_mfma_f32_16x16x32_bf16 v[144:147], v[128:131], v[168:171], v[152:155]
	v_mfma_f32_16x16x32_bf16 v[64:67], v[140:143], v[172:175], v[64:67]
	v_mfma_f32_16x16x32_bf16 v[148:151], v[128:131], v[176:179], v[156:159]
	v_mfma_f32_16x16x32_bf16 v[56:59], v[140:143], v[180:183], v[56:59]
	v_mfma_f32_16x16x32_bf16 v[76:79], v[132:135], v[188:191], v[76:79]
	v_mfma_f32_16x16x32_bf16 v[72:75], v[140:143], v[188:191], v[72:75]
	v_mfma_f32_16x16x32_bf16 v[144:147], v[132:135], v[172:175], v[144:147]
	v_mfma_f32_16x16x32_bf16 v[148:151], v[132:135], v[180:183], v[148:151]
	s_setprio 0
	s_barrier
	s_add_i32 s87, s89, s73
	v_lshl_add_u64 v[220:221], s[62:63], 0, v[194:195]
	s_mov_b32 m0, s87
	ds_read_b128 v[152:155], v247 offset:16384
	ds_read_b128 v[156:159], v247 offset:17408
	ds_read_b128 v[168:171], v247 offset:18432
	ds_read_b128 v[172:175], v247 offset:19456
	ds_read_b128 v[176:179], v247 offset:20480
	ds_read_b128 v[180:183], v247 offset:21504
	ds_read_b128 v[184:187], v247 offset:22528
	ds_read_b128 v[188:191], v247 offset:23552
	global_load_lds_dwordx4 v[220:221], off
	s_add_i32 m0, s87, 0x2000
	s_add_u32 s96, s62, 0x40000
	v_lshl_add_u64 v[222:223], s[62:63], 0, v[200:201]
	s_addc_u32 s97, s63, 0
	s_add_i32 s87, s90, s73
	global_load_lds_dwordx4 v[222:223], off
	v_lshl_add_u64 v[224:225], s[96:97], 0, v[194:195]
	s_mov_b32 m0, s87
	v_lshl_add_u64 v[226:227], s[64:65], 0, v[198:199]
	global_load_lds_dwordx4 v[224:225], off
	v_lshl_add_u64 v[224:225], s[96:97], 0, v[200:201]
	s_add_i32 m0, s87, 0x2000
	s_nop 0
	global_load_lds_dwordx4 v[224:225], off
	v_lshl_add_u64 v[224:225], s[64:65], 0, v[192:193]
	s_mov_b32 m0, s74
	s_nop 0
	global_load_lds_dwordx4 v[224:225], off
	s_mov_b32 m0, s75
	s_nop 0
	global_load_lds_dwordx4 v[226:227], off
	s_waitcnt vmcnt(8)
	s_waitcnt lgkmcnt(0)
	s_barrier
	s_setprio 1
	s_waitcnt lgkmcnt(0)
	v_mfma_f32_16x16x32_bf16 v[112:115], v[108:111], v[152:155], v[112:115]
	v_mfma_f32_16x16x32_bf16 v[20:23], v[120:123], v[152:155], v[20:23]
	v_mfma_f32_16x16x32_bf16 v[104:107], v[108:111], v[168:171], v[104:107]
	v_mfma_f32_16x16x32_bf16 v[16:19], v[120:123], v[168:171], v[16:19]
	v_mfma_f32_16x16x32_bf16 v[92:95], v[108:111], v[176:179], v[92:95]
	v_mfma_f32_16x16x32_bf16 v[4:7], v[120:123], v[176:179], v[4:7]
	v_mfma_f32_16x16x32_bf16 v[48:51], v[108:111], v[184:187], v[48:51]
	v_mfma_f32_16x16x32_bf16 v[40:43], v[120:123], v[184:187], v[40:43]
	v_mfma_f32_16x16x32_bf16 v[112:115], v[116:119], v[156:159], v[112:115]
	v_mfma_f32_16x16x32_bf16 v[20:23], v[124:127], v[156:159], v[20:23]
	v_mfma_f32_16x16x32_bf16 v[104:107], v[116:119], v[172:175], v[104:107]
	v_mfma_f32_16x16x32_bf16 v[16:19], v[124:127], v[172:175], v[16:19]
	v_mfma_f32_16x16x32_bf16 v[92:95], v[116:119], v[180:183], v[92:95]
	v_mfma_f32_16x16x32_bf16 v[4:7], v[124:127], v[180:183], v[4:7]
	v_mfma_f32_16x16x32_bf16 v[48:51], v[116:119], v[188:191], v[48:51]
	v_mfma_f32_16x16x32_bf16 v[40:43], v[124:127], v[188:191], v[40:43]
	s_setprio 0
	s_setprio 1
	v_mfma_f32_16x16x32_bf16 v[100:103], v[128:131], v[152:155], v[100:103]
	v_mfma_f32_16x16x32_bf16 v[12:15], v[136:139], v[152:155], v[12:15]
	v_mfma_f32_16x16x32_bf16 v[96:99], v[128:131], v[168:171], v[96:99]
	v_mfma_f32_16x16x32_bf16 v[8:11], v[136:139], v[168:171], v[8:11]
	v_mfma_f32_16x16x32_bf16 v[88:91], v[128:131], v[176:179], v[88:91]
	v_mfma_f32_16x16x32_bf16 v[0:3], v[136:139], v[176:179], v[0:3]
	v_mfma_f32_16x16x32_bf16 v[32:35], v[128:131], v[184:187], v[32:35]
	v_mfma_f32_16x16x32_bf16 v[24:27], v[136:139], v[184:187], v[24:27]
	v_mfma_f32_16x16x32_bf16 v[100:103], v[132:135], v[156:159], v[100:103]
	v_mfma_f32_16x16x32_bf16 v[12:15], v[140:143], v[156:159], v[12:15]
	v_mfma_f32_16x16x32_bf16 v[96:99], v[132:135], v[172:175], v[96:99]
	v_mfma_f32_16x16x32_bf16 v[8:11], v[140:143], v[172:175], v[8:11]
	v_mfma_f32_16x16x32_bf16 v[88:91], v[132:135], v[180:183], v[88:91]
	v_mfma_f32_16x16x32_bf16 v[0:3], v[140:143], v[180:183], v[0:3]
	v_mfma_f32_16x16x32_bf16 v[32:35], v[132:135], v[188:191], v[32:35]
	v_mfma_f32_16x16x32_bf16 v[24:27], v[140:143], v[188:191], v[24:27]
	s_setprio 0
	s_barrier
	s_add_i32 s87, 0, 0x18000
	s_add_i32 s96, 0, 0x1c000
	v_add_u32_e32 v124, s87, v205
	v_add_u32_e32 v140, s96, v205
	ds_read_b128 v[108:111], v124
	ds_read_b128 v[116:119], v124 offset:1024
	ds_read_b128 v[120:123], v124 offset:2048
	ds_read_b128 v[124:127], v124 offset:3072
	ds_read_b128 v[128:131], v140
	ds_read_b128 v[132:135], v140 offset:1024
	ds_read_b128 v[136:139], v140 offset:2048
	ds_read_b128 v[140:143], v140 offset:3072
	s_add_u32 s64, s64, 0x40000
	s_addc_u32 s65, s65, 0
	s_mov_b32 m0, s76
	v_lshl_add_u64 v[228:229], s[64:65], 0, v[192:193]
	ds_read_b128 v[152:155], v247 offset:32768
	ds_read_b128 v[156:159], v247 offset:33792
	ds_read_b128 v[168:171], v247 offset:34816
	ds_read_b128 v[172:175], v247 offset:35840
	ds_read_b128 v[176:179], v247 offset:36864
	ds_read_b128 v[180:183], v247 offset:37888
	ds_read_b128 v[184:187], v247 offset:38912
	ds_read_b128 v[188:191], v247 offset:39936
	global_load_lds_dwordx4 v[228:229], off
	v_lshl_add_u64 v[228:229], s[64:65], 0, v[198:199]
	s_mov_b32 m0, s77
	s_nop 0
	global_load_lds_dwordx4 v[228:229], off
	s_waitcnt vmcnt(8)
	s_waitcnt lgkmcnt(0)
	s_barrier
	s_setprio 1
	s_waitcnt lgkmcnt(0)
	v_mfma_f32_16x16x32_bf16 v[52:55], v[108:111], v[152:155], v[52:55]
	v_mfma_f32_16x16x32_bf16 v[44:47], v[120:123], v[152:155], v[44:47]
	v_mfma_f32_16x16x32_bf16 v[164:167], v[108:111], v[168:171], v[164:167]
	v_mfma_f32_16x16x32_bf16 v[68:71], v[120:123], v[168:171], v[68:71]
	v_mfma_f32_16x16x32_bf16 v[160:163], v[108:111], v[176:179], v[160:163]
	v_mfma_f32_16x16x32_bf16 v[60:63], v[120:123], v[176:179], v[60:63]
	v_mfma_f32_16x16x32_bf16 v[84:87], v[108:111], v[184:187], v[84:87]
	v_mfma_f32_16x16x32_bf16 v[80:83], v[120:123], v[184:187], v[80:83]
	v_mfma_f32_16x16x32_bf16 v[52:55], v[116:119], v[156:159], v[52:55]
	v_mfma_f32_16x16x32_bf16 v[44:47], v[124:127], v[156:159], v[44:47]
	v_mfma_f32_16x16x32_bf16 v[164:167], v[116:119], v[172:175], v[164:167]
	v_mfma_f32_16x16x32_bf16 v[68:71], v[124:127], v[172:175], v[68:71]
	v_mfma_f32_16x16x32_bf16 v[160:163], v[116:119], v[180:183], v[160:163]
	v_mfma_f32_16x16x32_bf16 v[60:63], v[124:127], v[180:183], v[60:63]
	v_mfma_f32_16x16x32_bf16 v[84:87], v[116:119], v[188:191], v[84:87]
	v_mfma_f32_16x16x32_bf16 v[80:83], v[124:127], v[188:191], v[80:83]
	s_setprio 0
	s_setprio 1
	v_mfma_f32_16x16x32_bf16 v[144:147], v[128:131], v[168:171], v[144:147]
	v_mfma_f32_16x16x32_bf16 v[36:39], v[128:131], v[152:155], v[36:39]
	v_mfma_f32_16x16x32_bf16 v[28:31], v[136:139], v[152:155], v[28:31]
	v_mfma_f32_16x16x32_bf16 v[152:155], v[132:135], v[172:175], v[144:147]
	v_mfma_f32_16x16x32_bf16 v[64:67], v[136:139], v[168:171], v[64:67]
	v_mfma_f32_16x16x32_bf16 v[144:147], v[128:131], v[176:179], v[148:151]
	v_mfma_f32_16x16x32_bf16 v[56:59], v[136:139], v[176:179], v[56:59]
	v_mfma_f32_16x16x32_bf16 v[76:79], v[128:131], v[184:187], v[76:79]
	v_mfma_f32_16x16x32_bf16 v[72:75], v[136:139], v[184:187], v[72:75]
	v_mfma_f32_16x16x32_bf16 v[36:39], v[132:135], v[156:159], v[36:39]
	v_mfma_f32_16x16x32_bf16 v[28:31], v[140:143], v[156:159], v[28:31]
	v_mfma_f32_16x16x32_bf16 v[64:67], v[140:143], v[172:175], v[64:67]
	v_mfma_f32_16x16x32_bf16 v[156:159], v[132:135], v[180:183], v[144:147]
	v_mfma_f32_16x16x32_bf16 v[56:59], v[140:143], v[180:183], v[56:59]
	v_mfma_f32_16x16x32_bf16 v[76:79], v[132:135], v[188:191], v[76:79]
	v_mfma_f32_16x16x32_bf16 v[72:75], v[140:143], v[188:191], v[72:75]
	s_setprio 0
	s_barrier
	s_add_i32 s64, s87, s73
	v_lshl_add_u64 v[220:221], v[220:221], 0, s[20:21]
	s_mov_b32 m0, s64
	ds_read_b128 v[144:147], v247 offset:49152
	ds_read_b128 v[148:151], v247 offset:50176
	ds_read_b128 v[168:171], v247 offset:51200
	ds_read_b128 v[172:175], v247 offset:52224
	ds_read_b128 v[176:179], v247 offset:53248
	ds_read_b128 v[180:183], v247 offset:54272
	ds_read_b128 v[184:187], v247 offset:55296
	ds_read_b128 v[188:191], v247 offset:56320
	global_load_lds_dwordx4 v[220:221], off
	s_add_i32 m0, s64, 0x2000
	s_add_u32 s62, s62, 0x40080
	v_lshl_add_u64 v[220:221], v[222:223], 0, s[20:21]
	s_addc_u32 s63, s63, 0
	s_add_i32 s64, s96, s73
	global_load_lds_dwordx4 v[220:221], off
	v_lshl_add_u64 v[220:221], s[62:63], 0, v[194:195]
	s_mov_b32 m0, s64
	s_nop 0
	global_load_lds_dwordx4 v[220:221], off
	v_lshl_add_u64 v[220:221], s[62:63], 0, v[200:201]
	s_add_i32 m0, s64, 0x2000
	s_nop 0
	global_load_lds_dwordx4 v[220:221], off
	v_lshl_add_u64 v[220:221], v[224:225], 0, s[20:21]
	s_mov_b32 m0, s80
	s_nop 0
	global_load_lds_dwordx4 v[220:221], off
	v_lshl_add_u64 v[220:221], v[226:227], 0, s[20:21]
	s_mov_b32 m0, s81
	s_nop 0
	global_load_lds_dwordx4 v[220:221], off
	s_waitcnt vmcnt(8)
	s_waitcnt lgkmcnt(0)
	s_barrier
	s_setprio 1
	s_waitcnt lgkmcnt(0)
	v_mfma_f32_16x16x32_bf16 v[112:115], v[108:111], v[144:147], v[112:115]
	v_mfma_f32_16x16x32_bf16 v[20:23], v[120:123], v[144:147], v[20:23]
	v_mfma_f32_16x16x32_bf16 v[104:107], v[108:111], v[168:171], v[104:107]
	v_mfma_f32_16x16x32_bf16 v[16:19], v[120:123], v[168:171], v[16:19]
	v_mfma_f32_16x16x32_bf16 v[92:95], v[108:111], v[176:179], v[92:95]
	v_mfma_f32_16x16x32_bf16 v[4:7], v[120:123], v[176:179], v[4:7]
	v_mfma_f32_16x16x32_bf16 v[48:51], v[108:111], v[184:187], v[48:51]
	v_mfma_f32_16x16x32_bf16 v[40:43], v[120:123], v[184:187], v[40:43]
	v_mfma_f32_16x16x32_bf16 v[112:115], v[116:119], v[148:151], v[112:115]
	v_mfma_f32_16x16x32_bf16 v[20:23], v[124:127], v[148:151], v[20:23]
	v_mfma_f32_16x16x32_bf16 v[104:107], v[116:119], v[172:175], v[104:107]
	v_mfma_f32_16x16x32_bf16 v[16:19], v[124:127], v[172:175], v[16:19]
	v_mfma_f32_16x16x32_bf16 v[92:95], v[116:119], v[180:183], v[92:95]
	v_mfma_f32_16x16x32_bf16 v[4:7], v[124:127], v[180:183], v[4:7]
	v_mfma_f32_16x16x32_bf16 v[48:51], v[116:119], v[188:191], v[48:51]
	v_mfma_f32_16x16x32_bf16 v[40:43], v[124:127], v[188:191], v[40:43]
	s_setprio 0
	s_setprio 1
	v_mfma_f32_16x16x32_bf16 v[100:103], v[128:131], v[144:147], v[100:103]
	v_mfma_f32_16x16x32_bf16 v[12:15], v[136:139], v[144:147], v[12:15]
	v_mfma_f32_16x16x32_bf16 v[96:99], v[128:131], v[168:171], v[96:99]
	v_mfma_f32_16x16x32_bf16 v[8:11], v[136:139], v[168:171], v[8:11]
	v_mfma_f32_16x16x32_bf16 v[88:91], v[128:131], v[176:179], v[88:91]
	v_mfma_f32_16x16x32_bf16 v[0:3], v[136:139], v[176:179], v[0:3]
	v_mfma_f32_16x16x32_bf16 v[32:35], v[128:131], v[184:187], v[32:35]
	v_mfma_f32_16x16x32_bf16 v[24:27], v[136:139], v[184:187], v[24:27]
	v_mfma_f32_16x16x32_bf16 v[100:103], v[132:135], v[148:151], v[100:103]
	v_mfma_f32_16x16x32_bf16 v[12:15], v[140:143], v[148:151], v[12:15]
	v_mfma_f32_16x16x32_bf16 v[96:99], v[132:135], v[172:175], v[96:99]
	v_mfma_f32_16x16x32_bf16 v[8:11], v[140:143], v[172:175], v[8:11]
	v_mfma_f32_16x16x32_bf16 v[88:91], v[132:135], v[180:183], v[88:91]
	v_mfma_f32_16x16x32_bf16 v[0:3], v[140:143], v[180:183], v[0:3]
	v_mfma_f32_16x16x32_bf16 v[32:35], v[132:135], v[188:191], v[32:35]
	v_mfma_f32_16x16x32_bf16 v[24:27], v[140:143], v[188:191], v[24:27]
	s_add_i32 s86, s86, 2
	s_add_u32 s8, s8, 0x100
	s_addc_u32 s9, s9, 0
	s_add_u32 s59, s59, 0x100
	s_addc_u32 s61, s61, 0
	s_cmp_gt_u32 s86, 13
	s_setprio 0
	s_barrier
	s_cbranch_scc0 .LBB0_577
	s_and_b64 vcc, exec, s[26:27]
	s_cbranch_vccz .LBB0_580
	s_barrier

.Lp6_nopf:
	s_waitcnt lgkmcnt(0)
	s_barrier
	s_setprio 1
	s_waitcnt lgkmcnt(0)
	v_mfma_f32_16x16x32_bf16 v[124:127], v[128:131], v[160:163], v[124:127]
	v_mfma_f32_16x16x32_bf16 v[120:123], v[136:139], v[160:163], v[120:123]
	v_mfma_f32_16x16x32_bf16 v[112:115], v[128:131], v[184:187], v[112:115]
	v_mfma_f32_16x16x32_bf16 v[104:107], v[136:139], v[184:187], v[104:107]
	v_mfma_f32_16x16x32_bf16 v[96:99], v[128:131], v[198:201], v[96:99]
	v_mfma_f32_16x16x32_bf16 v[88:91], v[136:139], v[198:201], v[88:91]
	v_mfma_f32_16x16x32_bf16 v[80:83], v[128:131], v[206:209], v[80:83]
	v_mfma_f32_16x16x32_bf16 v[72:75], v[136:139], v[206:209], v[72:75]
	v_mfma_f32_16x16x32_bf16 v[124:127], v[132:135], v[180:183], v[124:127]
	v_mfma_f32_16x16x32_bf16 v[120:123], v[140:143], v[180:183], v[120:123]
	v_mfma_f32_16x16x32_bf16 v[112:115], v[132:135], v[188:191], v[112:115]
	v_mfma_f32_16x16x32_bf16 v[104:107], v[140:143], v[188:191], v[104:107]
	v_mfma_f32_16x16x32_bf16 v[96:99], v[132:135], v[202:205], v[96:99]
	v_mfma_f32_16x16x32_bf16 v[88:91], v[140:143], v[202:205], v[88:91]
	v_mfma_f32_16x16x32_bf16 v[80:83], v[132:135], v[210:213], v[80:83]
	v_mfma_f32_16x16x32_bf16 v[72:75], v[140:143], v[210:213], v[72:75]
	s_setprio 0
	s_setprio 1
	v_mfma_f32_16x16x32_bf16 v[116:119], v[144:147], v[160:163], v[116:119]
	v_mfma_f32_16x16x32_bf16 v[108:111], v[152:155], v[160:163], v[108:111]
	v_mfma_f32_16x16x32_bf16 v[100:103], v[144:147], v[184:187], v[100:103]
	v_mfma_f32_16x16x32_bf16 v[92:95], v[152:155], v[184:187], v[92:95]
	v_mfma_f32_16x16x32_bf16 v[84:87], v[144:147], v[198:201], v[84:87]
	v_mfma_f32_16x16x32_bf16 v[76:79], v[152:155], v[198:201], v[76:79]
	v_mfma_f32_16x16x32_bf16 v[68:71], v[144:147], v[206:209], v[68:71]
	v_mfma_f32_16x16x32_bf16 v[64:67], v[152:155], v[206:209], v[64:67]
	v_mfma_f32_16x16x32_bf16 v[116:119], v[148:151], v[180:183], v[116:119]
	v_mfma_f32_16x16x32_bf16 v[108:111], v[156:159], v[180:183], v[108:111]
	v_mfma_f32_16x16x32_bf16 v[100:103], v[148:151], v[188:191], v[100:103]
	v_mfma_f32_16x16x32_bf16 v[92:95], v[156:159], v[188:191], v[92:95]
	v_mfma_f32_16x16x32_bf16 v[84:87], v[148:151], v[202:205], v[84:87]
	v_mfma_f32_16x16x32_bf16 v[76:79], v[156:159], v[202:205], v[76:79]
	v_mfma_f32_16x16x32_bf16 v[68:71], v[148:151], v[210:213], v[68:71]
	v_mfma_f32_16x16x32_bf16 v[64:67], v[156:159], v[210:213], v[64:67]
	s_setprio 0
	s_barrier
	s_add_i32 s18, s39, s28
	v_lshl_add_u64 v[214:215], s[22:23], 0, v[166:167]
	s_mov_b32 m0, s18
	ds_read_b128 v[160:163], v197 offset:16384
	ds_read_b128 v[180:183], v197 offset:17408
	ds_read_b128 v[184:187], v197 offset:18432
	ds_read_b128 v[188:191], v197 offset:19456
	ds_read_b128 v[198:201], v197 offset:20480
	ds_read_b128 v[202:205], v197 offset:21504
	ds_read_b128 v[206:209], v197 offset:22528
	ds_read_b128 v[210:213], v197 offset:23552
	global_load_lds_dwordx4 v[214:215], off
	s_add_i32 m0, s18, 0x2000
	s_add_u32 s18, s22, 0xb0000
	v_lshl_add_u64 v[216:217], s[22:23], 0, v[170:171]
	s_addc_u32 s19, s23, 0
	s_add_i32 s48, s40, s28
	global_load_lds_dwordx4 v[216:217], off
	v_lshl_add_u64 v[218:219], s[18:19], 0, v[166:167]
	s_mov_b32 m0, s48
	v_lshl_add_u64 v[220:221], s[24:25], 0, v[168:169]
	global_load_lds_dwordx4 v[218:219], off
	v_lshl_add_u64 v[218:219], s[18:19], 0, v[170:171]
	s_add_i32 m0, s48, 0x2000
	s_nop 0
	global_load_lds_dwordx4 v[218:219], off
	v_lshl_add_u64 v[218:219], s[24:25], 0, v[164:165]
	s_mov_b32 m0, s29
	s_nop 0
	global_load_lds_dwordx4 v[218:219], off
	s_mov_b32 m0, s33
	s_nop 0
	global_load_lds_dwordx4 v[220:221], off
	s_waitcnt vmcnt(8)
	s_waitcnt lgkmcnt(0)
	s_barrier
	s_setprio 1
	s_waitcnt lgkmcnt(0)
	v_mfma_f32_16x16x32_bf16 v[60:63], v[128:131], v[160:163], v[60:63]
	v_mfma_f32_16x16x32_bf16 v[56:59], v[136:139], v[160:163], v[56:59]
	v_mfma_f32_16x16x32_bf16 v[48:51], v[128:131], v[184:187], v[48:51]
	v_mfma_f32_16x16x32_bf16 v[40:43], v[136:139], v[184:187], v[40:43]
	v_mfma_f32_16x16x32_bf16 v[32:35], v[128:131], v[198:201], v[32:35]
	v_mfma_f32_16x16x32_bf16 v[24:27], v[136:139], v[198:201], v[24:27]
	v_mfma_f32_16x16x32_bf16 v[16:19], v[128:131], v[206:209], v[16:19]
	v_mfma_f32_16x16x32_bf16 v[8:11], v[136:139], v[206:209], v[8:11]
	v_mfma_f32_16x16x32_bf16 v[60:63], v[132:135], v[180:183], v[60:63]
	v_mfma_f32_16x16x32_bf16 v[56:59], v[140:143], v[180:183], v[56:59]
	v_mfma_f32_16x16x32_bf16 v[48:51], v[132:135], v[188:191], v[48:51]
	v_mfma_f32_16x16x32_bf16 v[40:43], v[140:143], v[188:191], v[40:43]
	v_mfma_f32_16x16x32_bf16 v[32:35], v[132:135], v[202:205], v[32:35]
	v_mfma_f32_16x16x32_bf16 v[24:27], v[140:143], v[202:205], v[24:27]
	v_mfma_f32_16x16x32_bf16 v[16:19], v[132:135], v[210:213], v[16:19]
	v_mfma_f32_16x16x32_bf16 v[8:11], v[140:143], v[210:213], v[8:11]
	s_setprio 0
	s_setprio 1
	v_mfma_f32_16x16x32_bf16 v[52:55], v[144:147], v[160:163], v[52:55]
	v_mfma_f32_16x16x32_bf16 v[44:47], v[152:155], v[160:163], v[44:47]
	v_mfma_f32_16x16x32_bf16 v[36:39], v[144:147], v[184:187], v[36:39]
	v_mfma_f32_16x16x32_bf16 v[28:31], v[152:155], v[184:187], v[28:31]
	v_mfma_f32_16x16x32_bf16 v[20:23], v[144:147], v[198:201], v[20:23]
	v_mfma_f32_16x16x32_bf16 v[12:15], v[152:155], v[198:201], v[12:15]
	v_mfma_f32_16x16x32_bf16 v[4:7], v[144:147], v[206:209], v[4:7]
	v_mfma_f32_16x16x32_bf16 v[0:3], v[152:155], v[206:209], v[0:3]
	v_mfma_f32_16x16x32_bf16 v[52:55], v[148:151], v[180:183], v[52:55]
	v_mfma_f32_16x16x32_bf16 v[44:47], v[156:159], v[180:183], v[44:47]
	v_mfma_f32_16x16x32_bf16 v[36:39], v[148:151], v[188:191], v[36:39]
	v_mfma_f32_16x16x32_bf16 v[28:31], v[156:159], v[188:191], v[28:31]
	v_mfma_f32_16x16x32_bf16 v[20:23], v[148:151], v[202:205], v[20:23]
	v_mfma_f32_16x16x32_bf16 v[12:15], v[156:159], v[202:205], v[12:15]
	v_mfma_f32_16x16x32_bf16 v[4:7], v[148:151], v[210:213], v[4:7]
	v_mfma_f32_16x16x32_bf16 v[0:3], v[156:159], v[210:213], v[0:3]
	s_setprio 0
	s_barrier
	s_add_i32 s48, 0, 0x18000
	s_add_i32 s49, 0, 0x1c000
	v_add_u32_e32 v140, s48, v193
	v_add_u32_e32 v156, s49, v193
	ds_read_b128 v[128:131], v140
	ds_read_b128 v[132:135], v140 offset:1024
	ds_read_b128 v[136:139], v140 offset:2048
	ds_read_b128 v[140:143], v140 offset:3072
	ds_read_b128 v[144:147], v156
	ds_read_b128 v[148:151], v156 offset:1024
	ds_read_b128 v[152:155], v156 offset:2048
	ds_read_b128 v[156:159], v156 offset:3072
	s_add_u32 s18, s24, 0xb0000
	s_addc_u32 s19, s25, 0
	s_mov_b32 m0, s34
	v_lshl_add_u64 v[222:223], s[18:19], 0, v[164:165]
	ds_read_b128 v[160:163], v197 offset:32768
	ds_read_b128 v[180:183], v197 offset:33792
	ds_read_b128 v[184:187], v197 offset:34816
	ds_read_b128 v[188:191], v197 offset:35840
	ds_read_b128 v[198:201], v197 offset:36864
	ds_read_b128 v[202:205], v197 offset:37888
	ds_read_b128 v[206:209], v197 offset:38912
	ds_read_b128 v[210:213], v197 offset:39936
	global_load_lds_dwordx4 v[222:223], off
	v_lshl_add_u64 v[222:223], s[18:19], 0, v[168:169]
	s_mov_b32 m0, s35
	s_nop 0
	global_load_lds_dwordx4 v[222:223], off
	s_waitcnt vmcnt(8)
	s_waitcnt lgkmcnt(0)
	s_barrier
	s_setprio 1
	s_waitcnt lgkmcnt(0)
	v_mfma_f32_16x16x32_bf16 v[124:127], v[128:131], v[160:163], v[124:127]
	v_mfma_f32_16x16x32_bf16 v[120:123], v[136:139], v[160:163], v[120:123]
	v_mfma_f32_16x16x32_bf16 v[112:115], v[128:131], v[184:187], v[112:115]
	v_mfma_f32_16x16x32_bf16 v[104:107], v[136:139], v[184:187], v[104:107]
	v_mfma_f32_16x16x32_bf16 v[96:99], v[128:131], v[198:201], v[96:99]
	v_mfma_f32_16x16x32_bf16 v[88:91], v[136:139], v[198:201], v[88:91]
	v_mfma_f32_16x16x32_bf16 v[80:83], v[128:131], v[206:209], v[80:83]
	v_mfma_f32_16x16x32_bf16 v[72:75], v[136:139], v[206:209], v[72:75]
	v_mfma_f32_16x16x32_bf16 v[124:127], v[132:135], v[180:183], v[124:127]
	v_mfma_f32_16x16x32_bf16 v[120:123], v[140:143], v[180:183], v[120:123]
	v_mfma_f32_16x16x32_bf16 v[112:115], v[132:135], v[188:191], v[112:115]
	v_mfma_f32_16x16x32_bf16 v[104:107], v[140:143], v[188:191], v[104:107]
	v_mfma_f32_16x16x32_bf16 v[96:99], v[132:135], v[202:205], v[96:99]
	v_mfma_f32_16x16x32_bf16 v[88:91], v[140:143], v[202:205], v[88:91]
	v_mfma_f32_16x16x32_bf16 v[80:83], v[132:135], v[210:213], v[80:83]
	v_mfma_f32_16x16x32_bf16 v[72:75], v[140:143], v[210:213], v[72:75]
	s_setprio 0
	s_setprio 1
	v_mfma_f32_16x16x32_bf16 v[116:119], v[144:147], v[160:163], v[116:119]
	v_mfma_f32_16x16x32_bf16 v[108:111], v[152:155], v[160:163], v[108:111]
	v_mfma_f32_16x16x32_bf16 v[100:103], v[144:147], v[184:187], v[100:103]
	v_mfma_f32_16x16x32_bf16 v[92:95], v[152:155], v[184:187], v[92:95]
	v_mfma_f32_16x16x32_bf16 v[84:87], v[144:147], v[198:201], v[84:87]
	v_mfma_f32_16x16x32_bf16 v[76:79], v[152:155], v[198:201], v[76:79]
	v_mfma_f32_16x16x32_bf16 v[68:71], v[144:147], v[206:209], v[68:71]
	v_mfma_f32_16x16x32_bf16 v[64:67], v[152:155], v[206:209], v[64:67]
	v_mfma_f32_16x16x32_bf16 v[116:119], v[148:151], v[180:183], v[116:119]
	v_mfma_f32_16x16x32_bf16 v[108:111], v[156:159], v[180:183], v[108:111]
	v_mfma_f32_16x16x32_bf16 v[100:103], v[148:151], v[188:191], v[100:103]
	v_mfma_f32_16x16x32_bf16 v[92:95], v[156:159], v[188:191], v[92:95]
	v_mfma_f32_16x16x32_bf16 v[84:87], v[148:151], v[202:205], v[84:87]
	v_mfma_f32_16x16x32_bf16 v[76:79], v[156:159], v[202:205], v[76:79]
	v_mfma_f32_16x16x32_bf16 v[68:71], v[148:151], v[210:213], v[68:71]
	v_mfma_f32_16x16x32_bf16 v[64:67], v[156:159], v[210:213], v[64:67]
	s_setprio 0
	s_barrier
	s_add_i32 s18, s48, s28
	v_lshl_add_u64 v[214:215], v[214:215], 0, s[10:11]
	s_mov_b32 m0, s18
	ds_read_b128 v[160:163], v197 offset:49152
	ds_read_b128 v[180:183], v197 offset:50176
	ds_read_b128 v[184:187], v197 offset:51200
	ds_read_b128 v[188:191], v197 offset:52224
	ds_read_b128 v[198:201], v197 offset:53248
	ds_read_b128 v[202:205], v197 offset:54272
	ds_read_b128 v[206:209], v197 offset:55296
	ds_read_b128 v[210:213], v197 offset:56320
	global_load_lds_dwordx4 v[214:215], off
	s_add_i32 m0, s18, 0x2000
	s_add_u32 s18, s22, 0xb0080
	v_lshl_add_u64 v[214:215], v[216:217], 0, s[10:11]
	s_addc_u32 s19, s23, 0
	s_add_i32 s22, s49, s28
	global_load_lds_dwordx4 v[214:215], off
	v_lshl_add_u64 v[214:215], s[18:19], 0, v[166:167]
	s_mov_b32 m0, s22
	s_nop 0
	global_load_lds_dwordx4 v[214:215], off
	v_lshl_add_u64 v[214:215], s[18:19], 0, v[170:171]
	s_add_i32 m0, s22, 0x2000
	s_nop 0
	global_load_lds_dwordx4 v[214:215], off
	v_lshl_add_u64 v[214:215], v[218:219], 0, s[10:11]
	s_mov_b32 m0, s37
	s_nop 0
	global_load_lds_dwordx4 v[214:215], off
	v_lshl_add_u64 v[214:215], v[220:221], 0, s[10:11]
	s_mov_b32 m0, s38
	s_nop 0
	global_load_lds_dwordx4 v[214:215], off
	s_waitcnt vmcnt(8)
	s_waitcnt lgkmcnt(0)
	s_barrier
	s_setprio 1
	s_waitcnt lgkmcnt(0)
	v_mfma_f32_16x16x32_bf16 v[60:63], v[128:131], v[160:163], v[60:63]
	v_mfma_f32_16x16x32_bf16 v[56:59], v[136:139], v[160:163], v[56:59]
	v_mfma_f32_16x16x32_bf16 v[48:51], v[128:131], v[184:187], v[48:51]
	v_mfma_f32_16x16x32_bf16 v[40:43], v[136:139], v[184:187], v[40:43]
	v_mfma_f32_16x16x32_bf16 v[32:35], v[128:131], v[198:201], v[32:35]
	v_mfma_f32_16x16x32_bf16 v[24:27], v[136:139], v[198:201], v[24:27]
	v_mfma_f32_16x16x32_bf16 v[16:19], v[128:131], v[206:209], v[16:19]
	v_mfma_f32_16x16x32_bf16 v[8:11], v[136:139], v[206:209], v[8:11]
	v_mfma_f32_16x16x32_bf16 v[60:63], v[132:135], v[180:183], v[60:63]
	v_mfma_f32_16x16x32_bf16 v[56:59], v[140:143], v[180:183], v[56:59]
	v_mfma_f32_16x16x32_bf16 v[48:51], v[132:135], v[188:191], v[48:51]
	v_mfma_f32_16x16x32_bf16 v[40:43], v[140:143], v[188:191], v[40:43]
	v_mfma_f32_16x16x32_bf16 v[32:35], v[132:135], v[202:205], v[32:35]
	v_mfma_f32_16x16x32_bf16 v[24:27], v[140:143], v[202:205], v[24:27]
	v_mfma_f32_16x16x32_bf16 v[16:19], v[132:135], v[210:213], v[16:19]
	v_mfma_f32_16x16x32_bf16 v[8:11], v[140:143], v[210:213], v[8:11]
	s_setprio 0
	s_setprio 1
	v_mfma_f32_16x16x32_bf16 v[52:55], v[144:147], v[160:163], v[52:55]
	v_mfma_f32_16x16x32_bf16 v[44:47], v[152:155], v[160:163], v[44:47]
	v_mfma_f32_16x16x32_bf16 v[36:39], v[144:147], v[184:187], v[36:39]
	v_mfma_f32_16x16x32_bf16 v[28:31], v[152:155], v[184:187], v[28:31]
	v_mfma_f32_16x16x32_bf16 v[20:23], v[144:147], v[198:201], v[20:23]
	v_mfma_f32_16x16x32_bf16 v[12:15], v[152:155], v[198:201], v[12:15]
	v_mfma_f32_16x16x32_bf16 v[4:7], v[144:147], v[206:209], v[4:7]
	v_mfma_f32_16x16x32_bf16 v[0:3], v[152:155], v[206:209], v[0:3]
	v_mfma_f32_16x16x32_bf16 v[52:55], v[148:151], v[180:183], v[52:55]
	v_mfma_f32_16x16x32_bf16 v[44:47], v[156:159], v[180:183], v[44:47]
	v_mfma_f32_16x16x32_bf16 v[36:39], v[148:151], v[188:191], v[36:39]
	v_mfma_f32_16x16x32_bf16 v[28:31], v[156:159], v[188:191], v[28:31]
	v_mfma_f32_16x16x32_bf16 v[20:23], v[148:151], v[202:205], v[20:23]
	v_mfma_f32_16x16x32_bf16 v[12:15], v[156:159], v[202:205], v[12:15]
	v_mfma_f32_16x16x32_bf16 v[4:7], v[148:151], v[210:213], v[4:7]
	v_mfma_f32_16x16x32_bf16 v[0:3], v[156:159], v[210:213], v[0:3]
	s_add_i32 s47, s47, 2
	s_add_u32 s45, s45, 0x100
	s_addc_u32 s46, s46, 0
	s_cmp_gt_u32 s47, 41
	s_mov_b64 s[18:19], s[20:21]
	s_setprio 0
	s_barrier
	s_cbranch_scc0 .LBB0_687
	s_and_b64 vcc, exec, s[12:13]
	s_cbranch_vccz .LBB0_690
	s_barrier
